# dense-attn unrolled loop: row sums in 4 independent accumulators instead of one serial add chain
# speedup vs baseline: 1.0129x; 1.0129x over previous
; #define WAIT_BAR(N) asm volatile("s_waitcnt vmcnt(" #N ") lgkmcnt(0)\n\ts_barrier":::"memory")
;   #define DMA_K(t,slot) glds16(ksrc+(long)(t)*KVBLK*KP,(unsigned)__builtin_amdgcn_readfirstlane(kdst+(slot)))
;   #define DMA_V(t,slot) glds16(vsrc+(long)(t)*KVBLK*KP,(unsigned)__builtin_amdgcn_readfirstlane(vdst+(slot)))
;   #define CMASK(P0,P1,t) do{}while(0)
;   #define START(P0,P1) do{ _Pragma("unroll") for(int r=0;r<16;++r)P0[r]=__builtin_amdgcn_exp2f(P0[r]); }while(0)
;   #define ROT() do{sl_prev=sl_cur;sl_cur=sl_next;sl_next=(sl_next==(NSLOT-1)*SLOTB)?0:sl_next+SLOTB;}while(0)
;   #define CMASK(P0,P1,t) do{}while(0)
;   #define CMASK(P0,P1,t) do{}while(0)
; template<int THRL> __device__ __forceinline__ void attn_unit(int b,int h,int qb,const bf16*Q,const bf16*__restrict__ K,const bf16*__restrict__ V,bf16*O,float*gssrow,float mref,char*shm){
;     ...
;   float l_reg=0.f;f32x16 o[2];o[0]=f32x16{};o[1]=f32x16{};f32x16 negm;_Pragma("unroll") for(int r=0;r<16;++r)negm[r]=-mref;asm volatile("":"+v"(negm));
;     ...
;   f32x16 pA0,pA1,pB0,pB1;
;   int sl_prev=0,sl_cur=0,sl_next=SLOTB;
;     ...
;   DMA_K(2,2*SLOTB);
;   WAIT_BAR(3);
;   qkt(pA0,pA1,Kbase,qr,negm,r32,hi);asm volatile("s_nop 15\n\ts_nop 7":"+v"(pA0),"+v"(pA1));CMASK(pA0,pA1,0);
;   START(pA0,pA1);
;   _Pragma("unroll") for(int r=0;r<16;++r)pA1[r]=__builtin_amdgcn_exp2f(pA1[r]);
;   WAIT_BAR(0);
;   DMA_K(3,0);DMA_V(1,SLOTB);
;   ROT();
;   kload8(kf,kp0+sl_cur);
;   WAIT_BAR(2);
;   s16x4 vlo[8],vhi[8]; u32x4 pw0,pw1,pw2,pw3;
.LBB0_449:
	s_lshl_b64 s[20:21], s[54:55], 1
	v_readlane_b32 s12, v254, 60
	s_add_u32 s20, s12, s20
	v_readlane_b32 s12, v254, 61
	s_addc_u32 s21, s12, s21
	s_add_u32 s20, s20, s50
	s_addc_u32 s21, s21, s51
	s_add_u32 s20, s20, s48
	v_exp_f32_e32 v48, v0
	v_lshlrev_b32_e32 v0, 1, v194
	s_addc_u32 s21, s21, s49
	v_and_b32_e32 v202, 32, v0
	v_lshlrev_b32_e32 v0, 4, v194
	v_lshl_add_u64 v[190:191], s[20:21], 0, v[128:129]
	s_lshl_b64 s[20:21], s[52:53], 1
	v_and_b32_e32 v0, 0xc0, v0
	s_add_u32 s20, s20, s50
	v_lshl_or_b32 v198, v197, 8, v0
	v_add_u32_e32 v0, 0, v202
	s_addc_u32 s21, s21, s51
	v_add3_u32 v199, v0, v201, v198
	v_and_b32_e32 v0, 3, v194
	s_add_u32 s20, s20, s48
	v_lshlrev_b32_e32 v128, 4, v0
	s_addc_u32 s21, s21, s49
	v_exp_f32_e32 v49, v1
	v_lshl_add_u64 v[0:1], s[20:21], 0, v[128:129]
	s_lshl_b32 s20, s15, 6
	v_exp_f32_e32 v64, v16
	v_exp_f32_e32 v65, v17
	v_exp_f32_e32 v66, v18
	v_exp_f32_e32 v67, v19
	v_exp_f32_e32 v68, v20
	v_exp_f32_e32 v69, v21
	v_exp_f32_e32 v70, v22
	v_exp_f32_e32 v71, v23
	v_exp_f32_e32 v72, v24
	v_exp_f32_e32 v73, v25
	v_exp_f32_e32 v74, v26
	v_exp_f32_e32 v75, v27
	v_exp_f32_e32 v76, v28
	v_exp_f32_e32 v77, v29
	v_exp_f32_e32 v78, v30
	v_exp_f32_e32 v79, v31
	v_exp_f32_e32 v50, v2
	v_exp_f32_e32 v51, v3
	v_exp_f32_e32 v52, v4
	v_exp_f32_e32 v53, v5
	v_exp_f32_e32 v54, v6
	v_exp_f32_e32 v55, v7
	v_exp_f32_e32 v56, v8
	v_exp_f32_e32 v57, v9
	v_exp_f32_e32 v58, v10
	v_exp_f32_e32 v59, v11
	v_exp_f32_e32 v60, v12
	v_exp_f32_e32 v61, v13
	v_exp_f32_e32 v62, v14
	v_exp_f32_e32 v63, v15
	s_and_b32 s20, s20, 0x3000
	v_lshl_or_b32 v128, v84, 8, s20
	v_readlane_b32 s12, v254, 62
	v_lshl_add_u64 v[0:1], v[0:1], 0, v[128:129]
	v_readlane_b32 s13, v254, 63
	v_mov_b32_e32 v203, 0
	s_movk_i32 s29, 0x4000
	v_lshl_add_u64 v[192:193], s[12:13], 0, v[0:1]
	s_movk_i32 s21, 0x2000
	s_mov_b32 s31, 0
	s_mov_b32 s20, -1
	v_mov_b32_e32 v0, 0
	v_mov_b32_e32 v1, v203
	v_mov_b32_e32 v2, v203
	v_mov_b32_e32 v3, v203
	v_mov_b32_e32 v4, v203
	v_mov_b32_e32 v5, v203
	v_mov_b32_e32 v6, v203
	v_mov_b32_e32 v7, v203
	v_mov_b32_e32 v8, v203
	v_mov_b32_e32 v9, v203
	v_mov_b32_e32 v10, v203
	v_mov_b32_e32 v11, v203
	v_mov_b32_e32 v12, v203
	v_mov_b32_e32 v13, v203
	v_mov_b32_e32 v14, v203
	v_mov_b32_e32 v15, v203
	v_mov_b32_e32 v16, 0
	v_mov_b32_e32 v17, v203
	v_mov_b32_e32 v18, v203
	v_mov_b32_e32 v19, v203
	v_mov_b32_e32 v20, v203
	v_mov_b32_e32 v21, v203
	v_mov_b32_e32 v22, v203
	v_mov_b32_e32 v23, v203
	v_mov_b32_e32 v24, v203
	v_mov_b32_e32 v25, v203
	v_mov_b32_e32 v26, v203
	v_mov_b32_e32 v27, v203
	v_mov_b32_e32 v28, v203
	v_mov_b32_e32 v29, v203
	v_mov_b32_e32 v30, v203
	v_mov_b32_e32 v31, v203
	v_readfirstlane_b32 s98, v190
	v_readfirstlane_b32 s99, v191
	v_readfirstlane_b32 s100, v192
	v_readfirstlane_b32 s101, v193
	v_subrev_u32_e32 v216, s98, v190
	v_subrev_u32_e32 v217, s100, v192
	v_add_u32_e32 v218, 0x10000, v216
	v_add_u32_e32 v216, 0xc000, v216
	v_add_u32_e32 v219, 0x8000, v217
	v_add_u32_e32 v217, 0x4000, v217
	v_mov_b32_e32 v220, 0
	v_mov_b32_e32 v221, 0
	v_mov_b32_e32 v222, 0
	v_mov_b32_e32 v223, 0
.Lattn6:
	ds_read_b64_tr_b16 v[204:205], v199 offset:24576
	ds_read_b64_tr_b16 v[206:207], v199 offset:25088
	v_add_f32_e32 v220, v64, v220
	v_add_f32_e32 v221, v65, v221
	v_add_f32_e32 v222, v66, v222
	v_add_f32_e32 v223, v67, v223
	v_add_f32_e32 v220, v68, v220
	v_add_f32_e32 v221, v69, v221
	v_cvt_pk_bf16_f32 v154, v64, v65
	v_cvt_pk_bf16_f32 v155, v66, v67
	v_mfma_f32_32x32x16_bf16 v[96:111], v[80:83], v[158:161], v[32:47]
	ds_read_b64_tr_b16 v[64:65], v199 offset:28672
	ds_read_b64_tr_b16 v[66:67], v199 offset:29184
	v_add_f32_e32 v222, v70, v222
	v_add_f32_e32 v223, v71, v223
	v_add_f32_e32 v220, v72, v220
	v_add_f32_e32 v221, v73, v221
	v_mfma_f32_32x32x16_bf16 v[80:95], v[166:169], v[158:161], v[32:47]
	v_cvt_pk_bf16_f32 v156, v68, v69
	v_cvt_pk_bf16_f32 v157, v70, v71
	ds_read_b64_tr_b16 v[68:69], v199 offset:25600
	ds_read_b64_tr_b16 v[70:71], v199 offset:26112
	v_add_f32_e32 v222, v74, v222
	v_add_f32_e32 v223, v75, v223
	v_add_f32_e32 v220, v76, v220
	v_add_f32_e32 v221, v77, v221
	v_cvt_pk_bf16_f32 v146, v72, v73
	v_cvt_pk_bf16_f32 v147, v74, v75
	v_mfma_f32_32x32x16_bf16 v[96:111], v[170:173], v[150:153], v[96:111]
	ds_read_b64_tr_b16 v[72:73], v199 offset:29696
	ds_read_b64_tr_b16 v[74:75], v199 offset:30208
	v_mfma_f32_32x32x16_bf16 v[80:95], v[162:165], v[150:153], v[80:95]
	v_add_f32_e32 v222, v78, v222
	v_add_f32_e32 v223, v79, v223
	v_add_f32_e32 v220, v48, v220
	v_add_f32_e32 v221, v49, v221
	v_cvt_pk_bf16_f32 v148, v76, v77
	v_cvt_pk_bf16_f32 v149, v78, v79
	ds_read_b64_tr_b16 v[76:77], v199 offset:26624
	ds_read_b64_tr_b16 v[78:79], v199 offset:27136
	v_mfma_f32_32x32x16_bf16 v[96:111], v[124:127], v[142:145], v[96:111]
	v_add_f32_e32 v222, v50, v222
	v_add_f32_e32 v223, v51, v223
	v_add_f32_e32 v220, v52, v220
	v_add_f32_e32 v221, v53, v221
	v_cvt_pk_bf16_f32 v138, v48, v49
	v_cvt_pk_bf16_f32 v139, v50, v51
	ds_read_b64_tr_b16 v[48:49], v199 offset:30720
	ds_read_b64_tr_b16 v[50:51], v199 offset:31232
	v_mfma_f32_32x32x16_bf16 v[80:95], v[120:123], v[142:145], v[80:95]
	v_add_f32_e32 v222, v54, v222
	v_add_f32_e32 v223, v55, v223
	v_add_f32_e32 v220, v56, v220
	v_add_f32_e32 v221, v57, v221
	v_cvt_pk_bf16_f32 v140, v52, v53
	v_cvt_pk_bf16_f32 v141, v54, v55
	ds_read_b64_tr_b16 v[52:53], v199 offset:27648
	ds_read_b64_tr_b16 v[54:55], v199 offset:28160
	v_mfma_f32_32x32x16_bf16 v[96:111], v[116:119], v[134:137], v[96:111]
	v_add_f32_e32 v222, v58, v222
	v_add_f32_e32 v223, v59, v223
	v_add_f32_e32 v220, v60, v220
	v_add_f32_e32 v221, v61, v221
	v_cvt_pk_bf16_f32 v130, v56, v57
	v_cvt_pk_bf16_f32 v131, v58, v59
	ds_read_b64_tr_b16 v[56:57], v199 offset:31744
	ds_read_b64_tr_b16 v[58:59], v199 offset:32256
	v_mfma_f32_32x32x16_bf16 v[80:95], v[112:115], v[134:137], v[80:95]
	v_add_f32_e32 v222, v62, v222
	v_add_f32_e32 v223, v63, v223
	v_cvt_pk_bf16_f32 v132, v60, v61
	v_cvt_pk_bf16_f32 v133, v62, v63
	s_add_i32 m0, s5, 0x2000
	s_nop 0
	global_load_lds_dwordx4 v216, s[98:99]
	s_add_i32 m0, s4, 0x4000
	s_nop 0
	global_load_lds_dwordx4 v217, s[100:101]
	s_waitcnt lgkmcnt(14)
	v_mfma_f32_32x32x16_bf16 v[0:15], v[154:157], v[204:207], v[0:15]
	v_exp_f32_e32 v96, v96
	v_exp_f32_e32 v97, v97
	v_exp_f32_e32 v98, v98
	v_exp_f32_e32 v99, v99
	s_waitcnt lgkmcnt(12)
	v_mfma_f32_32x32x16_bf16 v[16:31], v[154:157], v[64:67], v[16:31]
	v_exp_f32_e32 v100, v100
	v_exp_f32_e32 v101, v101
	v_exp_f32_e32 v102, v102
	v_exp_f32_e32 v103, v103
	ds_read_b128 v[60:63], v200 offset:16384
	ds_read_b128 v[116:119], v200 offset:16896
	s_waitcnt lgkmcnt(12)
	v_mfma_f32_32x32x16_bf16 v[0:15], v[146:149], v[68:71], v[0:15]
	v_exp_f32_e32 v104, v104
	v_exp_f32_e32 v105, v105
	v_exp_f32_e32 v106, v106
	v_exp_f32_e32 v107, v107
	ds_read_b128 v[120:123], v200 offset:18432
	ds_read_b128 v[124:127], v200 offset:18944
	s_waitcnt lgkmcnt(12)
	v_mfma_f32_32x32x16_bf16 v[16:31], v[146:149], v[72:75], v[16:31]
	v_exp_f32_e32 v108, v108
	v_exp_f32_e32 v109, v109
	v_exp_f32_e32 v110, v110
	v_exp_f32_e32 v111, v111
	ds_read_b128 v[162:165], v200 offset:20480
	ds_read_b128 v[166:169], v200 offset:20992
	s_waitcnt lgkmcnt(12)
	v_mfma_f32_32x32x16_bf16 v[0:15], v[138:141], v[76:79], v[0:15]
	v_exp_f32_e32 v80, v80
	v_exp_f32_e32 v81, v81
	v_exp_f32_e32 v82, v82
	v_exp_f32_e32 v83, v83
	ds_read_b128 v[170:173], v200 offset:22528
	ds_read_b128 v[112:115], v200 offset:23040
	s_waitcnt lgkmcnt(12)
	v_mfma_f32_32x32x16_bf16 v[16:31], v[138:141], v[48:51], v[16:31]
	v_exp_f32_e32 v84, v84
	v_exp_f32_e32 v85, v85
	v_exp_f32_e32 v86, v86
	v_exp_f32_e32 v87, v87
	s_waitcnt lgkmcnt(10)
	v_mfma_f32_32x32x16_bf16 v[0:15], v[130:133], v[52:55], v[0:15]
	v_exp_f32_e32 v88, v88
	v_exp_f32_e32 v89, v89
	v_exp_f32_e32 v90, v90
	v_exp_f32_e32 v91, v91
	s_waitcnt lgkmcnt(8)
	v_mfma_f32_32x32x16_bf16 v[16:31], v[130:133], v[56:59], v[16:31]
	v_exp_f32_e32 v92, v92
	v_exp_f32_e32 v93, v93
	v_exp_f32_e32 v94, v94
	v_exp_f32_e32 v95, v95
	s_waitcnt vmcnt(2) lgkmcnt(0)
	s_barrier
	ds_read_b64_tr_b16 v[204:205], v199 offset:32768
	ds_read_b64_tr_b16 v[206:207], v199 offset:33280
	v_mfma_f32_32x32x16_bf16 v[64:79], v[60:63], v[158:161], v[32:47]
	v_add_f32_e32 v220, v96, v220
	v_add_f32_e32 v221, v97, v221
	v_add_f32_e32 v222, v98, v222
	v_add_f32_e32 v223, v99, v223
	v_add_f32_e32 v220, v100, v220
	v_add_f32_e32 v221, v101, v221
	v_cvt_pk_bf16_f32 v154, v96, v97
	v_cvt_pk_bf16_f32 v155, v98, v99
	ds_read_b64_tr_b16 v[96:97], v199 offset:36864
	ds_read_b64_tr_b16 v[98:99], v199 offset:37376
	v_add_f32_e32 v222, v102, v222
	v_add_f32_e32 v223, v103, v223
	v_add_f32_e32 v220, v104, v220
	v_add_f32_e32 v221, v105, v221
	v_mfma_f32_32x32x16_bf16 v[48:63], v[116:119], v[158:161], v[32:47]
	v_cvt_pk_bf16_f32 v156, v100, v101
	v_cvt_pk_bf16_f32 v157, v102, v103
	ds_read_b64_tr_b16 v[100:101], v199 offset:33792
	ds_read_b64_tr_b16 v[102:103], v199 offset:34304
	v_mfma_f32_32x32x16_bf16 v[64:79], v[120:123], v[150:153], v[64:79]
	v_add_f32_e32 v222, v106, v222
	v_add_f32_e32 v223, v107, v223
	v_add_f32_e32 v220, v108, v220
	v_add_f32_e32 v221, v109, v221
	v_cvt_pk_bf16_f32 v146, v104, v105
	v_cvt_pk_bf16_f32 v147, v106, v107
	ds_read_b64_tr_b16 v[104:105], v199 offset:37888
	ds_read_b64_tr_b16 v[106:107], v199 offset:38400
	v_mfma_f32_32x32x16_bf16 v[48:63], v[124:127], v[150:153], v[48:63]
	v_add_f32_e32 v222, v110, v222
	v_add_f32_e32 v223, v111, v223
	v_add_f32_e32 v220, v80, v220
	v_add_f32_e32 v221, v81, v221
	v_cvt_pk_bf16_f32 v148, v108, v109
	v_cvt_pk_bf16_f32 v149, v110, v111
	ds_read_b64_tr_b16 v[108:109], v199 offset:34816
	ds_read_b64_tr_b16 v[110:111], v199 offset:35328
	v_mfma_f32_32x32x16_bf16 v[64:79], v[162:165], v[142:145], v[64:79]
	v_add_f32_e32 v222, v82, v222
	v_add_f32_e32 v223, v83, v223
	v_add_f32_e32 v220, v84, v220
	v_add_f32_e32 v221, v85, v221
	v_cvt_pk_bf16_f32 v138, v80, v81
	v_cvt_pk_bf16_f32 v139, v82, v83
	ds_read_b64_tr_b16 v[208:209], v199 offset:38912
	ds_read_b64_tr_b16 v[210:211], v199 offset:39424
	v_mfma_f32_32x32x16_bf16 v[48:63], v[166:169], v[142:145], v[48:63]
	v_add_f32_e32 v222, v86, v222
	v_add_f32_e32 v223, v87, v223
	v_add_f32_e32 v220, v88, v220
	v_add_f32_e32 v221, v89, v221
	v_cvt_pk_bf16_f32 v140, v84, v85
	v_cvt_pk_bf16_f32 v141, v86, v87
	ds_read_b64_tr_b16 v[84:85], v199 offset:35840
	ds_read_b64_tr_b16 v[86:87], v199 offset:36352
	v_mfma_f32_32x32x16_bf16 v[64:79], v[170:173], v[134:137], v[64:79]
	v_add_f32_e32 v222, v90, v222
	v_add_f32_e32 v223, v91, v223
	v_add_f32_e32 v220, v92, v220
	v_add_f32_e32 v221, v93, v221
	v_cvt_pk_bf16_f32 v130, v88, v89
	v_cvt_pk_bf16_f32 v131, v90, v91
	ds_read_b64_tr_b16 v[88:89], v199 offset:39936
	ds_read_b64_tr_b16 v[90:91], v199 offset:40448
	v_mfma_f32_32x32x16_bf16 v[48:63], v[112:115], v[134:137], v[48:63]
	v_add_f32_e32 v222, v94, v222
	v_add_f32_e32 v223, v95, v223
	v_cvt_pk_bf16_f32 v132, v92, v93
	v_cvt_pk_bf16_f32 v133, v94, v95
	s_add_i32 m0, s5, 0x4000
	s_nop 0
	global_load_lds_dwordx4 v218, s[98:99]
	s_mov_b32 m0, s4
	s_nop 0
	global_load_lds_dwordx4 v219, s[100:101]
	s_waitcnt lgkmcnt(14)
	v_mfma_f32_32x32x16_bf16 v[0:15], v[154:157], v[204:207], v[0:15]
	v_exp_f32_e32 v64, v64
	v_exp_f32_e32 v65, v65
	v_exp_f32_e32 v66, v66
	v_exp_f32_e32 v67, v67
	s_waitcnt lgkmcnt(12)
	v_mfma_f32_32x32x16_bf16 v[16:31], v[154:157], v[96:99], v[16:31]
	v_exp_f32_e32 v68, v68
	v_exp_f32_e32 v69, v69
	v_exp_f32_e32 v70, v70
	v_exp_f32_e32 v71, v71
	ds_read_b128 v[80:83], v200
	ds_read_b128 v[166:169], v200 offset:512
	s_waitcnt lgkmcnt(12)
	v_mfma_f32_32x32x16_bf16 v[0:15], v[146:149], v[100:103], v[0:15]
	v_exp_f32_e32 v72, v72
	v_exp_f32_e32 v73, v73
	v_exp_f32_e32 v74, v74
	v_exp_f32_e32 v75, v75
	ds_read_b128 v[170:173], v200 offset:2048
	ds_read_b128 v[162:165], v200 offset:2560
	s_waitcnt lgkmcnt(12)
	v_mfma_f32_32x32x16_bf16 v[16:31], v[146:149], v[104:107], v[16:31]
	v_exp_f32_e32 v76, v76
	v_exp_f32_e32 v77, v77
	v_exp_f32_e32 v78, v78
	v_exp_f32_e32 v79, v79
	ds_read_b128 v[124:127], v200 offset:4096
	ds_read_b128 v[120:123], v200 offset:4608
	s_waitcnt lgkmcnt(12)
	v_mfma_f32_32x32x16_bf16 v[0:15], v[138:141], v[108:111], v[0:15]
	v_exp_f32_e32 v48, v48
	v_exp_f32_e32 v49, v49
	v_exp_f32_e32 v50, v50
	v_exp_f32_e32 v51, v51
	ds_read_b128 v[116:119], v200 offset:6144
	ds_read_b128 v[112:115], v200 offset:6656
	s_waitcnt lgkmcnt(12)
	v_mfma_f32_32x32x16_bf16 v[16:31], v[138:141], v[208:211], v[16:31]
	v_exp_f32_e32 v52, v52
	v_exp_f32_e32 v53, v53
	v_exp_f32_e32 v54, v54
	v_exp_f32_e32 v55, v55
	s_waitcnt lgkmcnt(10)
	v_mfma_f32_32x32x16_bf16 v[0:15], v[130:133], v[84:87], v[0:15]
	v_exp_f32_e32 v56, v56
	v_exp_f32_e32 v57, v57
	v_exp_f32_e32 v58, v58
	v_exp_f32_e32 v59, v59
	s_waitcnt lgkmcnt(8)
	v_mfma_f32_32x32x16_bf16 v[16:31], v[130:133], v[88:91], v[16:31]
	v_exp_f32_e32 v60, v60
	v_exp_f32_e32 v61, v61
	v_exp_f32_e32 v62, v62
	v_exp_f32_e32 v63, v63
	s_waitcnt vmcnt(2) lgkmcnt(0)
	s_barrier
	s_add_u32 s98, s98, 0x8000
	s_addc_u32 s99, s99, 0
	s_add_u32 s100, s100, 0x8000
	s_addc_u32 s101, s101, 0
	ds_read_b64_tr_b16 v[204:205], v199 offset:40960
	ds_read_b64_tr_b16 v[206:207], v199 offset:41472
	v_add_f32_e32 v220, v64, v220
	v_add_f32_e32 v221, v65, v221
	v_add_f32_e32 v222, v66, v222
	v_add_f32_e32 v223, v67, v223
	v_add_f32_e32 v220, v68, v220
	v_add_f32_e32 v221, v69, v221
	v_cvt_pk_bf16_f32 v154, v64, v65
	v_cvt_pk_bf16_f32 v155, v66, v67
	v_mfma_f32_32x32x16_bf16 v[96:111], v[80:83], v[158:161], v[32:47]
	ds_read_b64_tr_b16 v[64:65], v199 offset:45056
	ds_read_b64_tr_b16 v[66:67], v199 offset:45568
	v_add_f32_e32 v222, v70, v222
	v_add_f32_e32 v223, v71, v223
	v_add_f32_e32 v220, v72, v220
	v_add_f32_e32 v221, v73, v221
	v_mfma_f32_32x32x16_bf16 v[80:95], v[166:169], v[158:161], v[32:47]
	v_cvt_pk_bf16_f32 v156, v68, v69
	v_cvt_pk_bf16_f32 v157, v70, v71
	ds_read_b64_tr_b16 v[68:69], v199 offset:41984
	ds_read_b64_tr_b16 v[70:71], v199 offset:42496
	v_add_f32_e32 v222, v74, v222
	v_add_f32_e32 v223, v75, v223
	v_add_f32_e32 v220, v76, v220
	v_add_f32_e32 v221, v77, v221
	v_cvt_pk_bf16_f32 v146, v72, v73
	v_cvt_pk_bf16_f32 v147, v74, v75
	v_mfma_f32_32x32x16_bf16 v[96:111], v[170:173], v[150:153], v[96:111]
	ds_read_b64_tr_b16 v[72:73], v199 offset:46080
	ds_read_b64_tr_b16 v[74:75], v199 offset:46592
	v_mfma_f32_32x32x16_bf16 v[80:95], v[162:165], v[150:153], v[80:95]
	v_add_f32_e32 v222, v78, v222
	v_add_f32_e32 v223, v79, v223
	v_add_f32_e32 v220, v48, v220
	v_add_f32_e32 v221, v49, v221
	v_cvt_pk_bf16_f32 v148, v76, v77
	v_cvt_pk_bf16_f32 v149, v78, v79
	ds_read_b64_tr_b16 v[76:77], v199 offset:43008
	ds_read_b64_tr_b16 v[78:79], v199 offset:43520
	v_mfma_f32_32x32x16_bf16 v[96:111], v[124:127], v[142:145], v[96:111]
	v_add_f32_e32 v222, v50, v222
	v_add_f32_e32 v223, v51, v223
	v_add_f32_e32 v220, v52, v220
	v_add_f32_e32 v221, v53, v221
	v_cvt_pk_bf16_f32 v138, v48, v49
	v_cvt_pk_bf16_f32 v139, v50, v51
	ds_read_b64_tr_b16 v[48:49], v199 offset:47104
	ds_read_b64_tr_b16 v[50:51], v199 offset:47616
	v_mfma_f32_32x32x16_bf16 v[80:95], v[120:123], v[142:145], v[80:95]
	v_add_f32_e32 v222, v54, v222
	v_add_f32_e32 v223, v55, v223
	v_add_f32_e32 v220, v56, v220
	v_add_f32_e32 v221, v57, v221
	v_cvt_pk_bf16_f32 v140, v52, v53
	v_cvt_pk_bf16_f32 v141, v54, v55
	ds_read_b64_tr_b16 v[52:53], v199 offset:44032
	ds_read_b64_tr_b16 v[54:55], v199 offset:44544
	v_mfma_f32_32x32x16_bf16 v[96:111], v[116:119], v[134:137], v[96:111]
	v_add_f32_e32 v222, v58, v222
	v_add_f32_e32 v223, v59, v223
	v_add_f32_e32 v220, v60, v220
	v_add_f32_e32 v221, v61, v221
	v_cvt_pk_bf16_f32 v130, v56, v57
	v_cvt_pk_bf16_f32 v131, v58, v59
	ds_read_b64_tr_b16 v[56:57], v199 offset:48128
	ds_read_b64_tr_b16 v[58:59], v199 offset:48640
	v_mfma_f32_32x32x16_bf16 v[80:95], v[112:115], v[134:137], v[80:95]
	v_add_f32_e32 v222, v62, v222
	v_add_f32_e32 v223, v63, v223
	v_cvt_pk_bf16_f32 v132, v60, v61
	v_cvt_pk_bf16_f32 v133, v62, v63
	s_mov_b32 m0, s5
	s_nop 0
	global_load_lds_dwordx4 v216, s[98:99]
	s_add_i32 m0, s4, 0x2000
	s_nop 0
	global_load_lds_dwordx4 v217, s[100:101]
	s_waitcnt lgkmcnt(14)
	v_mfma_f32_32x32x16_bf16 v[0:15], v[154:157], v[204:207], v[0:15]
	v_exp_f32_e32 v96, v96
	v_exp_f32_e32 v97, v97
	v_exp_f32_e32 v98, v98
	v_exp_f32_e32 v99, v99
	s_waitcnt lgkmcnt(12)
	v_mfma_f32_32x32x16_bf16 v[16:31], v[154:157], v[64:67], v[16:31]
	v_exp_f32_e32 v100, v100
	v_exp_f32_e32 v101, v101
	v_exp_f32_e32 v102, v102
	v_exp_f32_e32 v103, v103
	ds_read_b128 v[60:63], v200 offset:8192
	ds_read_b128 v[116:119], v200 offset:8704
	s_waitcnt lgkmcnt(12)
	v_mfma_f32_32x32x16_bf16 v[0:15], v[146:149], v[68:71], v[0:15]
	v_exp_f32_e32 v104, v104
	v_exp_f32_e32 v105, v105
	v_exp_f32_e32 v106, v106
	v_exp_f32_e32 v107, v107
	ds_read_b128 v[120:123], v200 offset:10240
	ds_read_b128 v[124:127], v200 offset:10752
	s_waitcnt lgkmcnt(12)
	v_mfma_f32_32x32x16_bf16 v[16:31], v[146:149], v[72:75], v[16:31]
	v_exp_f32_e32 v108, v108
	v_exp_f32_e32 v109, v109
	v_exp_f32_e32 v110, v110
	v_exp_f32_e32 v111, v111
	ds_read_b128 v[162:165], v200 offset:12288
	ds_read_b128 v[166:169], v200 offset:12800
	s_waitcnt lgkmcnt(12)
	v_mfma_f32_32x32x16_bf16 v[0:15], v[138:141], v[76:79], v[0:15]
	v_exp_f32_e32 v80, v80
	v_exp_f32_e32 v81, v81
	v_exp_f32_e32 v82, v82
	v_exp_f32_e32 v83, v83
	ds_read_b128 v[170:173], v200 offset:14336
	ds_read_b128 v[112:115], v200 offset:14848
	s_waitcnt lgkmcnt(12)
	v_mfma_f32_32x32x16_bf16 v[16:31], v[138:141], v[48:51], v[16:31]
	v_exp_f32_e32 v84, v84
	v_exp_f32_e32 v85, v85
	v_exp_f32_e32 v86, v86
	v_exp_f32_e32 v87, v87
	s_waitcnt lgkmcnt(10)
	v_mfma_f32_32x32x16_bf16 v[0:15], v[130:133], v[52:55], v[0:15]
	v_exp_f32_e32 v88, v88
	v_exp_f32_e32 v89, v89
	v_exp_f32_e32 v90, v90
	v_exp_f32_e32 v91, v91
	s_waitcnt lgkmcnt(8)
	v_mfma_f32_32x32x16_bf16 v[16:31], v[130:133], v[56:59], v[16:31]
	v_exp_f32_e32 v92, v92
	v_exp_f32_e32 v93, v93
	v_exp_f32_e32 v94, v94
	v_exp_f32_e32 v95, v95
	s_waitcnt vmcnt(2) lgkmcnt(0)
	s_barrier
	ds_read_b64_tr_b16 v[204:205], v199 offset:24576
	ds_read_b64_tr_b16 v[206:207], v199 offset:25088
	v_mfma_f32_32x32x16_bf16 v[64:79], v[60:63], v[158:161], v[32:47]
	v_add_f32_e32 v220, v96, v220
	v_add_f32_e32 v221, v97, v221
	v_add_f32_e32 v222, v98, v222
	v_add_f32_e32 v223, v99, v223
	v_add_f32_e32 v220, v100, v220
	v_add_f32_e32 v221, v101, v221
	v_cvt_pk_bf16_f32 v154, v96, v97
	v_cvt_pk_bf16_f32 v155, v98, v99
	ds_read_b64_tr_b16 v[96:97], v199 offset:28672
	ds_read_b64_tr_b16 v[98:99], v199 offset:29184
	v_add_f32_e32 v222, v102, v222
	v_add_f32_e32 v223, v103, v223
	v_add_f32_e32 v220, v104, v220
	v_add_f32_e32 v221, v105, v221
	v_mfma_f32_32x32x16_bf16 v[48:63], v[116:119], v[158:161], v[32:47]
	v_cvt_pk_bf16_f32 v156, v100, v101
	v_cvt_pk_bf16_f32 v157, v102, v103
	ds_read_b64_tr_b16 v[100:101], v199 offset:25600
	ds_read_b64_tr_b16 v[102:103], v199 offset:26112
	v_mfma_f32_32x32x16_bf16 v[64:79], v[120:123], v[150:153], v[64:79]
	v_add_f32_e32 v222, v106, v222
	v_add_f32_e32 v223, v107, v223
	v_add_f32_e32 v220, v108, v220
	v_add_f32_e32 v221, v109, v221
	v_cvt_pk_bf16_f32 v146, v104, v105
	v_cvt_pk_bf16_f32 v147, v106, v107
	ds_read_b64_tr_b16 v[104:105], v199 offset:29696
	ds_read_b64_tr_b16 v[106:107], v199 offset:30208
	v_mfma_f32_32x32x16_bf16 v[48:63], v[124:127], v[150:153], v[48:63]
	v_add_f32_e32 v222, v110, v222
	v_add_f32_e32 v223, v111, v223
	v_add_f32_e32 v220, v80, v220
	v_add_f32_e32 v221, v81, v221
	v_cvt_pk_bf16_f32 v148, v108, v109
	v_cvt_pk_bf16_f32 v149, v110, v111
	ds_read_b64_tr_b16 v[108:109], v199 offset:26624
	ds_read_b64_tr_b16 v[110:111], v199 offset:27136
	v_mfma_f32_32x32x16_bf16 v[64:79], v[162:165], v[142:145], v[64:79]
	v_add_f32_e32 v222, v82, v222
	v_add_f32_e32 v223, v83, v223
	v_add_f32_e32 v220, v84, v220
	v_add_f32_e32 v221, v85, v221
	v_cvt_pk_bf16_f32 v138, v80, v81
	v_cvt_pk_bf16_f32 v139, v82, v83
	ds_read_b64_tr_b16 v[208:209], v199 offset:30720
	ds_read_b64_tr_b16 v[210:211], v199 offset:31232
	v_mfma_f32_32x32x16_bf16 v[48:63], v[166:169], v[142:145], v[48:63]
	v_add_f32_e32 v222, v86, v222
	v_add_f32_e32 v223, v87, v223
	v_add_f32_e32 v220, v88, v220
	v_add_f32_e32 v221, v89, v221
	v_cvt_pk_bf16_f32 v140, v84, v85
	v_cvt_pk_bf16_f32 v141, v86, v87
	ds_read_b64_tr_b16 v[84:85], v199 offset:27648
	ds_read_b64_tr_b16 v[86:87], v199 offset:28160
	v_mfma_f32_32x32x16_bf16 v[64:79], v[170:173], v[134:137], v[64:79]
	v_add_f32_e32 v222, v90, v222
	v_add_f32_e32 v223, v91, v223
	v_add_f32_e32 v220, v92, v220
	v_add_f32_e32 v221, v93, v221
	v_cvt_pk_bf16_f32 v130, v88, v89
	v_cvt_pk_bf16_f32 v131, v90, v91
	ds_read_b64_tr_b16 v[88:89], v199 offset:31744
	ds_read_b64_tr_b16 v[90:91], v199 offset:32256
	v_mfma_f32_32x32x16_bf16 v[48:63], v[112:115], v[134:137], v[48:63]
	v_add_f32_e32 v222, v94, v222
	v_add_f32_e32 v223, v95, v223
	v_cvt_pk_bf16_f32 v132, v92, v93
	v_cvt_pk_bf16_f32 v133, v94, v95
	s_add_i32 m0, s5, 0x2000
	s_nop 0
	global_load_lds_dwordx4 v218, s[98:99]
	s_add_i32 m0, s4, 0x4000
	s_nop 0
	global_load_lds_dwordx4 v219, s[100:101]
	s_waitcnt lgkmcnt(14)
	v_mfma_f32_32x32x16_bf16 v[0:15], v[154:157], v[204:207], v[0:15]
	v_exp_f32_e32 v64, v64
	v_exp_f32_e32 v65, v65
	v_exp_f32_e32 v66, v66
	v_exp_f32_e32 v67, v67
	s_waitcnt lgkmcnt(12)
	v_mfma_f32_32x32x16_bf16 v[16:31], v[154:157], v[96:99], v[16:31]
	v_exp_f32_e32 v68, v68
	v_exp_f32_e32 v69, v69
	v_exp_f32_e32 v70, v70
	v_exp_f32_e32 v71, v71
	ds_read_b128 v[80:83], v200 offset:16384
	ds_read_b128 v[166:169], v200 offset:16896
	s_waitcnt lgkmcnt(12)
	v_mfma_f32_32x32x16_bf16 v[0:15], v[146:149], v[100:103], v[0:15]
	v_exp_f32_e32 v72, v72
	v_exp_f32_e32 v73, v73
	v_exp_f32_e32 v74, v74
	v_exp_f32_e32 v75, v75
	ds_read_b128 v[170:173], v200 offset:18432
	ds_read_b128 v[162:165], v200 offset:18944
	s_waitcnt lgkmcnt(12)
	v_mfma_f32_32x32x16_bf16 v[16:31], v[146:149], v[104:107], v[16:31]
	v_exp_f32_e32 v76, v76
	v_exp_f32_e32 v77, v77
	v_exp_f32_e32 v78, v78
	v_exp_f32_e32 v79, v79
	ds_read_b128 v[124:127], v200 offset:20480
	ds_read_b128 v[120:123], v200 offset:20992
	s_waitcnt lgkmcnt(12)
	v_mfma_f32_32x32x16_bf16 v[0:15], v[138:141], v[108:111], v[0:15]
	v_exp_f32_e32 v48, v48
	v_exp_f32_e32 v49, v49
	v_exp_f32_e32 v50, v50
	v_exp_f32_e32 v51, v51
	ds_read_b128 v[116:119], v200 offset:22528
	ds_read_b128 v[112:115], v200 offset:23040
	s_waitcnt lgkmcnt(12)
	v_mfma_f32_32x32x16_bf16 v[16:31], v[138:141], v[208:211], v[16:31]
	v_exp_f32_e32 v52, v52
	v_exp_f32_e32 v53, v53
	v_exp_f32_e32 v54, v54
	v_exp_f32_e32 v55, v55
	s_waitcnt lgkmcnt(10)
	v_mfma_f32_32x32x16_bf16 v[0:15], v[130:133], v[84:87], v[0:15]
	v_exp_f32_e32 v56, v56
	v_exp_f32_e32 v57, v57
	v_exp_f32_e32 v58, v58
	v_exp_f32_e32 v59, v59
	s_waitcnt lgkmcnt(8)
	v_mfma_f32_32x32x16_bf16 v[16:31], v[130:133], v[88:91], v[16:31]
	v_exp_f32_e32 v60, v60
	v_exp_f32_e32 v61, v61
	v_exp_f32_e32 v62, v62
	v_exp_f32_e32 v63, v63
	s_waitcnt vmcnt(2) lgkmcnt(0)
	s_barrier
	s_add_u32 s98, s98, 0x8000
	s_addc_u32 s99, s99, 0
	s_add_u32 s100, s100, 0x8000
	s_addc_u32 s101, s101, 0
	ds_read_b64_tr_b16 v[204:205], v199 offset:32768
	ds_read_b64_tr_b16 v[206:207], v199 offset:33280
	v_add_f32_e32 v220, v64, v220
	v_add_f32_e32 v221, v65, v221
	v_add_f32_e32 v222, v66, v222
	v_add_f32_e32 v223, v67, v223
	v_add_f32_e32 v220, v68, v220
	v_add_f32_e32 v221, v69, v221
	v_cvt_pk_bf16_f32 v154, v64, v65
	v_cvt_pk_bf16_f32 v155, v66, v67
	v_mfma_f32_32x32x16_bf16 v[96:111], v[80:83], v[158:161], v[32:47]
	ds_read_b64_tr_b16 v[64:65], v199 offset:36864
	ds_read_b64_tr_b16 v[66:67], v199 offset:37376
	v_add_f32_e32 v222, v70, v222
	v_add_f32_e32 v223, v71, v223
	v_add_f32_e32 v220, v72, v220
	v_add_f32_e32 v221, v73, v221
	v_mfma_f32_32x32x16_bf16 v[80:95], v[166:169], v[158:161], v[32:47]
	v_cvt_pk_bf16_f32 v156, v68, v69
	v_cvt_pk_bf16_f32 v157, v70, v71
	ds_read_b64_tr_b16 v[68:69], v199 offset:33792
	ds_read_b64_tr_b16 v[70:71], v199 offset:34304
	v_add_f32_e32 v222, v74, v222
	v_add_f32_e32 v223, v75, v223
	v_add_f32_e32 v220, v76, v220
	v_add_f32_e32 v221, v77, v221
	v_cvt_pk_bf16_f32 v146, v72, v73
	v_cvt_pk_bf16_f32 v147, v74, v75
	v_mfma_f32_32x32x16_bf16 v[96:111], v[170:173], v[150:153], v[96:111]
	ds_read_b64_tr_b16 v[72:73], v199 offset:37888
	ds_read_b64_tr_b16 v[74:75], v199 offset:38400
	v_mfma_f32_32x32x16_bf16 v[80:95], v[162:165], v[150:153], v[80:95]
	v_add_f32_e32 v222, v78, v222
	v_add_f32_e32 v223, v79, v223
	v_add_f32_e32 v220, v48, v220
	v_add_f32_e32 v221, v49, v221
	v_cvt_pk_bf16_f32 v148, v76, v77
	v_cvt_pk_bf16_f32 v149, v78, v79
	ds_read_b64_tr_b16 v[76:77], v199 offset:34816
	ds_read_b64_tr_b16 v[78:79], v199 offset:35328
	v_mfma_f32_32x32x16_bf16 v[96:111], v[124:127], v[142:145], v[96:111]
	v_add_f32_e32 v222, v50, v222
	v_add_f32_e32 v223, v51, v223
	v_add_f32_e32 v220, v52, v220
	v_add_f32_e32 v221, v53, v221
	v_cvt_pk_bf16_f32 v138, v48, v49
	v_cvt_pk_bf16_f32 v139, v50, v51
	ds_read_b64_tr_b16 v[48:49], v199 offset:38912
	ds_read_b64_tr_b16 v[50:51], v199 offset:39424
	v_mfma_f32_32x32x16_bf16 v[80:95], v[120:123], v[142:145], v[80:95]
	v_add_f32_e32 v222, v54, v222
	v_add_f32_e32 v223, v55, v223
	v_add_f32_e32 v220, v56, v220
	v_add_f32_e32 v221, v57, v221
	v_cvt_pk_bf16_f32 v140, v52, v53
	v_cvt_pk_bf16_f32 v141, v54, v55
	ds_read_b64_tr_b16 v[52:53], v199 offset:35840
	ds_read_b64_tr_b16 v[54:55], v199 offset:36352
	v_mfma_f32_32x32x16_bf16 v[96:111], v[116:119], v[134:137], v[96:111]
	v_add_f32_e32 v222, v58, v222
	v_add_f32_e32 v223, v59, v223
	v_add_f32_e32 v220, v60, v220
	v_add_f32_e32 v221, v61, v221
	v_cvt_pk_bf16_f32 v130, v56, v57
	v_cvt_pk_bf16_f32 v131, v58, v59
	ds_read_b64_tr_b16 v[56:57], v199 offset:39936
	ds_read_b64_tr_b16 v[58:59], v199 offset:40448
	v_mfma_f32_32x32x16_bf16 v[80:95], v[112:115], v[134:137], v[80:95]
	v_add_f32_e32 v222, v62, v222
	v_add_f32_e32 v223, v63, v223
	v_cvt_pk_bf16_f32 v132, v60, v61
	v_cvt_pk_bf16_f32 v133, v62, v63
	s_add_i32 m0, s5, 0x4000
	s_nop 0
	global_load_lds_dwordx4 v216, s[98:99]
	s_mov_b32 m0, s4
	s_nop 0
	global_load_lds_dwordx4 v217, s[100:101]
	s_waitcnt lgkmcnt(14)
	v_mfma_f32_32x32x16_bf16 v[0:15], v[154:157], v[204:207], v[0:15]
	v_exp_f32_e32 v96, v96
	v_exp_f32_e32 v97, v97
	v_exp_f32_e32 v98, v98
	v_exp_f32_e32 v99, v99
	s_waitcnt lgkmcnt(12)
	v_mfma_f32_32x32x16_bf16 v[16:31], v[154:157], v[64:67], v[16:31]
	v_exp_f32_e32 v100, v100
	v_exp_f32_e32 v101, v101
	v_exp_f32_e32 v102, v102
	v_exp_f32_e32 v103, v103
	ds_read_b128 v[60:63], v200
	ds_read_b128 v[116:119], v200 offset:512
	s_waitcnt lgkmcnt(12)
	v_mfma_f32_32x32x16_bf16 v[0:15], v[146:149], v[68:71], v[0:15]
	v_exp_f32_e32 v104, v104
	v_exp_f32_e32 v105, v105
	v_exp_f32_e32 v106, v106
	v_exp_f32_e32 v107, v107
	ds_read_b128 v[120:123], v200 offset:2048
	ds_read_b128 v[124:127], v200 offset:2560
	s_waitcnt lgkmcnt(12)
	v_mfma_f32_32x32x16_bf16 v[16:31], v[146:149], v[72:75], v[16:31]
	v_exp_f32_e32 v108, v108
	v_exp_f32_e32 v109, v109
	v_exp_f32_e32 v110, v110
	v_exp_f32_e32 v111, v111
	ds_read_b128 v[162:165], v200 offset:4096
	ds_read_b128 v[166:169], v200 offset:4608
	s_waitcnt lgkmcnt(12)
	v_mfma_f32_32x32x16_bf16 v[0:15], v[138:141], v[76:79], v[0:15]
	v_exp_f32_e32 v80, v80
	v_exp_f32_e32 v81, v81
	v_exp_f32_e32 v82, v82
	v_exp_f32_e32 v83, v83
	ds_read_b128 v[170:173], v200 offset:6144
	ds_read_b128 v[112:115], v200 offset:6656
	s_waitcnt lgkmcnt(12)
	v_mfma_f32_32x32x16_bf16 v[16:31], v[138:141], v[48:51], v[16:31]
	v_exp_f32_e32 v84, v84
	v_exp_f32_e32 v85, v85
	v_exp_f32_e32 v86, v86
	v_exp_f32_e32 v87, v87
	s_waitcnt lgkmcnt(10)
	v_mfma_f32_32x32x16_bf16 v[0:15], v[130:133], v[52:55], v[0:15]
	v_exp_f32_e32 v88, v88
	v_exp_f32_e32 v89, v89
	v_exp_f32_e32 v90, v90
	v_exp_f32_e32 v91, v91
	s_waitcnt lgkmcnt(8)
	v_mfma_f32_32x32x16_bf16 v[16:31], v[130:133], v[56:59], v[16:31]
	v_exp_f32_e32 v92, v92
	v_exp_f32_e32 v93, v93
	v_exp_f32_e32 v94, v94
	v_exp_f32_e32 v95, v95
	s_waitcnt vmcnt(2) lgkmcnt(0)
	s_barrier
; #define WAIT_BAR(N) asm volatile("s_waitcnt vmcnt(" #N ") lgkmcnt(0)\n\ts_barrier":::"memory")
;   #define RESC() do{}while(0)
;   #define ROT() do{sl_prev=sl_cur;sl_cur=sl_next;sl_next=(sl_next==(NSLOT-1)*SLOTB)?0:sl_next+SLOTB;}while(0)
; template<int THRL> __device__ __forceinline__ void attn_unit(int b,int h,int qb,const bf16*Q,const bf16*__restrict__ K,const bf16*__restrict__ V,bf16*O,float*gssrow,float mref,char*shm){
;     ...
;   for(;t+5<NT;t+=2){
;     STEP(pB0,pB1,pA0,pA1,t,true,true,true);     WAIT_BAR(2); RESC(); ROT();
;     STEP(pA0,pA1,pB0,pB1,t+1,true,true,true);   WAIT_BAR(2); RESC(); ROT();
;   }
	ds_read_b64_tr_b16 v[204:205], v199 offset:40960
	ds_read_b64_tr_b16 v[206:207], v199 offset:41472
	v_mfma_f32_32x32x16_bf16 v[64:79], v[60:63], v[158:161], v[32:47]
	v_add_f32_e32 v220, v96, v220
	v_add_f32_e32 v221, v97, v221
	v_add_f32_e32 v222, v98, v222
	v_add_f32_e32 v223, v99, v223
	v_add_f32_e32 v220, v100, v220
	v_add_f32_e32 v221, v101, v221
	v_cvt_pk_bf16_f32 v154, v96, v97
	v_cvt_pk_bf16_f32 v155, v98, v99
	ds_read_b64_tr_b16 v[96:97], v199 offset:45056
	ds_read_b64_tr_b16 v[98:99], v199 offset:45568
	v_add_f32_e32 v222, v102, v222
	v_add_f32_e32 v223, v103, v223
	v_add_f32_e32 v220, v104, v220
	v_add_f32_e32 v221, v105, v221
	v_mfma_f32_32x32x16_bf16 v[48:63], v[116:119], v[158:161], v[32:47]
	v_cvt_pk_bf16_f32 v156, v100, v101
	v_cvt_pk_bf16_f32 v157, v102, v103
	ds_read_b64_tr_b16 v[100:101], v199 offset:41984
	ds_read_b64_tr_b16 v[102:103], v199 offset:42496
	v_mfma_f32_32x32x16_bf16 v[64:79], v[120:123], v[150:153], v[64:79]
	v_add_f32_e32 v222, v106, v222
	v_add_f32_e32 v223, v107, v223
	v_add_f32_e32 v220, v108, v220
	v_add_f32_e32 v221, v109, v221
	v_cvt_pk_bf16_f32 v146, v104, v105
	v_cvt_pk_bf16_f32 v147, v106, v107
	ds_read_b64_tr_b16 v[104:105], v199 offset:46080
	ds_read_b64_tr_b16 v[106:107], v199 offset:46592
	v_mfma_f32_32x32x16_bf16 v[48:63], v[124:127], v[150:153], v[48:63]
	v_add_f32_e32 v222, v110, v222
	v_add_f32_e32 v223, v111, v223
	v_add_f32_e32 v220, v80, v220
	v_add_f32_e32 v221, v81, v221
	v_cvt_pk_bf16_f32 v148, v108, v109
	v_cvt_pk_bf16_f32 v149, v110, v111
	ds_read_b64_tr_b16 v[108:109], v199 offset:43008
	ds_read_b64_tr_b16 v[110:111], v199 offset:43520
	v_mfma_f32_32x32x16_bf16 v[64:79], v[162:165], v[142:145], v[64:79]
	v_add_f32_e32 v222, v82, v222
	v_add_f32_e32 v223, v83, v223
	v_add_f32_e32 v220, v84, v220
	v_add_f32_e32 v221, v85, v221
	v_cvt_pk_bf16_f32 v138, v80, v81
	v_cvt_pk_bf16_f32 v139, v82, v83
	ds_read_b64_tr_b16 v[208:209], v199 offset:47104
	ds_read_b64_tr_b16 v[210:211], v199 offset:47616
	v_mfma_f32_32x32x16_bf16 v[48:63], v[166:169], v[142:145], v[48:63]
	v_add_f32_e32 v222, v86, v222
	v_add_f32_e32 v223, v87, v223
	v_add_f32_e32 v220, v88, v220
	v_add_f32_e32 v221, v89, v221
	v_cvt_pk_bf16_f32 v140, v84, v85
	v_cvt_pk_bf16_f32 v141, v86, v87
	ds_read_b64_tr_b16 v[84:85], v199 offset:44032
	ds_read_b64_tr_b16 v[86:87], v199 offset:44544
	v_mfma_f32_32x32x16_bf16 v[64:79], v[170:173], v[134:137], v[64:79]
	v_add_f32_e32 v222, v90, v222
	v_add_f32_e32 v223, v91, v223
	v_add_f32_e32 v220, v92, v220
	v_add_f32_e32 v221, v93, v221
	v_cvt_pk_bf16_f32 v130, v88, v89
	v_cvt_pk_bf16_f32 v131, v90, v91
	ds_read_b64_tr_b16 v[88:89], v199 offset:48128
	ds_read_b64_tr_b16 v[90:91], v199 offset:48640
	v_mfma_f32_32x32x16_bf16 v[48:63], v[112:115], v[134:137], v[48:63]
	v_add_f32_e32 v222, v94, v222
	v_add_f32_e32 v223, v95, v223
	v_cvt_pk_bf16_f32 v132, v92, v93
	v_cvt_pk_bf16_f32 v133, v94, v95
	s_mov_b32 m0, s5
	s_nop 0
	global_load_lds_dwordx4 v218, s[98:99]
	s_add_i32 m0, s4, 0x2000
	s_nop 0
	global_load_lds_dwordx4 v219, s[100:101]
	s_waitcnt lgkmcnt(14)
	v_mfma_f32_32x32x16_bf16 v[0:15], v[154:157], v[204:207], v[0:15]
	v_exp_f32_e32 v64, v64
	v_exp_f32_e32 v65, v65
	v_exp_f32_e32 v66, v66
	v_exp_f32_e32 v67, v67
	s_waitcnt lgkmcnt(12)
	v_mfma_f32_32x32x16_bf16 v[16:31], v[154:157], v[96:99], v[16:31]
	v_exp_f32_e32 v68, v68
	v_exp_f32_e32 v69, v69
	v_exp_f32_e32 v70, v70
	v_exp_f32_e32 v71, v71
	ds_read_b128 v[80:83], v200 offset:8192
	ds_read_b128 v[166:169], v200 offset:8704
	s_waitcnt lgkmcnt(12)
	v_mfma_f32_32x32x16_bf16 v[0:15], v[146:149], v[100:103], v[0:15]
	v_exp_f32_e32 v72, v72
	v_exp_f32_e32 v73, v73
	v_exp_f32_e32 v74, v74
	v_exp_f32_e32 v75, v75
	ds_read_b128 v[170:173], v200 offset:10240
	ds_read_b128 v[162:165], v200 offset:10752
	s_waitcnt lgkmcnt(12)
	v_mfma_f32_32x32x16_bf16 v[16:31], v[146:149], v[104:107], v[16:31]
	v_exp_f32_e32 v76, v76
	v_exp_f32_e32 v77, v77
	v_exp_f32_e32 v78, v78
	v_exp_f32_e32 v79, v79
	ds_read_b128 v[124:127], v200 offset:12288
	ds_read_b128 v[120:123], v200 offset:12800
	s_waitcnt lgkmcnt(12)
	v_mfma_f32_32x32x16_bf16 v[0:15], v[138:141], v[108:111], v[0:15]
	v_exp_f32_e32 v48, v48
	v_exp_f32_e32 v49, v49
	v_exp_f32_e32 v50, v50
	v_exp_f32_e32 v51, v51
	ds_read_b128 v[116:119], v200 offset:14336
	ds_read_b128 v[112:115], v200 offset:14848
	s_waitcnt lgkmcnt(12)
	v_mfma_f32_32x32x16_bf16 v[16:31], v[138:141], v[208:211], v[16:31]
	v_exp_f32_e32 v52, v52
	v_exp_f32_e32 v53, v53
	v_exp_f32_e32 v54, v54
	v_exp_f32_e32 v55, v55
	s_waitcnt lgkmcnt(10)
	v_mfma_f32_32x32x16_bf16 v[0:15], v[130:133], v[84:87], v[0:15]
	v_exp_f32_e32 v56, v56
	v_exp_f32_e32 v57, v57
	v_exp_f32_e32 v58, v58
	v_exp_f32_e32 v59, v59
	s_waitcnt lgkmcnt(8)
	v_mfma_f32_32x32x16_bf16 v[16:31], v[130:133], v[88:91], v[16:31]
	v_exp_f32_e32 v60, v60
	v_exp_f32_e32 v61, v61
	v_exp_f32_e32 v62, v62
	v_exp_f32_e32 v63, v63
	s_waitcnt vmcnt(2) lgkmcnt(0)
	s_barrier
	s_add_u32 s98, s98, 0x8000
	s_addc_u32 s99, s99, 0
	s_add_u32 s100, s100, 0x8000
	s_addc_u32 s101, s101, 0
	s_add_i32 s20, s20, 6
	s_cmpk_lg_i32 s20, 0xf5
	s_cbranch_scc1 .Lattn6
	v_add_f32_e32 v220, v220, v221
	v_add_f32_e32 v222, v222, v223
	v_add_f32_e32 v220, v220, v222
	v_add_f32_e32 v203, v203, v220
